# HG3 chunk loop: og gain loads hoisted to once per unit, over-conservative vmcnt(1) after next-chunk prefetch relaxed to vmcnt(18)
# baseline (speedup 1.0000x reference)
.LBB0_1444:
	v_or_b32_e32 v61, s93, v101
	v_cmp_le_i32_e32 vcc, v61, v66
	v_lshlrev_b32_e32 v64, 1, v61
	v_add3_u32 v64, s40, v64, v67
	s_nop 2
	v_cndmask_b32_e32 v56, 0, v56, vcc
	v_bfe_u32 v65, v56, 16, 1
	v_add3_u32 v56, v56, v65, s41
	v_cmp_le_i32_e32 vcc, v61, v68
	ds_write_b16_d16_hi v64, v56
	v_lshlrev_b32_e32 v98, 4, v100
	v_cndmask_b32_e32 v56, 0, v57, vcc
	v_bfe_u32 v57, v56, 16, 1
	v_add3_u32 v56, v56, v57, s41
	v_cmp_le_i32_e32 vcc, v61, v69
	ds_write_b16_d16_hi v64, v56 offset:144
	v_mul_u32_u24_e32 v99, 0x90, v101
	v_cndmask_b32_e32 v56, 0, v58, vcc
	v_bfe_u32 v57, v56, 16, 1
	v_add3_u32 v56, v56, v57, s41
	v_cmp_le_i32_e32 vcc, v61, v60
	ds_write_b16_d16_hi v64, v56 offset:288
	v_add3_u32 v106, s40, v98, v99
	v_cndmask_b32_e32 v56, 0, v59, vcc
	v_bfe_u32 v57, v56, 16, 1
	v_add3_u32 v56, v56, v57, s41
	ds_write_b16_d16_hi v64, v56 offset:432
	s_waitcnt lgkmcnt(0)
	s_barrier
	ds_read_b128 v[56:59], v106
	ds_read_b128 v[64:67], v106 offset:64
	s_waitcnt lgkmcnt(1)
	v_mfma_f32_16x16x32_bf16 v[56:59], v[56:59], v[48:51], 0
	v_add_u32_e32 v107, 16, v63
	v_mad_u64_u32 v[94:95], vcc, v107, s68, v[62:63]
	v_mad_u64_u32 v[92:93], vcc, v100, s96, v[62:63]
	ds_read_b64_tr_b16 v[62:63], v94
	ds_read_b64_tr_b16 v[60:61], v92
	s_waitcnt lgkmcnt(2)
	v_mfma_f32_16x16x32_bf16 v[56:59], v[64:67], v[44:47], v[56:59]
	v_cvt_pk_bf16_f32 v72, v0, v1
	v_cvt_pk_bf16_f32 v73, v2, v3
	v_cvt_pk_bf16_f32 v74, v4, v5
	v_cvt_pk_bf16_f32 v75, v6, v7
	ds_read_b64_tr_b16 v[78:79], v94 offset:2304
	ds_read_b64_tr_b16 v[80:81], v94 offset:4608
	s_waitcnt lgkmcnt(2)
	v_mfma_f32_16x16x32_bf16 v[56:59], v[60:63], v[72:75], v[56:59]
	v_cvt_pk_bf16_f32 v68, v12, v13
	v_cvt_pk_bf16_f32 v69, v14, v15
	v_cvt_pk_bf16_f32 v70, v8, v9
	v_cvt_pk_bf16_f32 v71, v10, v11
	ds_read_b64_tr_b16 v[64:65], v92 offset:9216
	ds_read_b64_tr_b16 v[66:67], v92 offset:11520
	s_waitcnt lgkmcnt(2)
	v_mfma_f32_16x16x32_bf16 v[56:59], v[78:81], v[68:71], v[56:59]
	v_cvt_pk_bf16_f32 v76, v20, v21
	v_cvt_pk_bf16_f32 v77, v22, v23
	v_cvt_pk_bf16_f32 v78, v16, v17
	v_cvt_pk_bf16_f32 v79, v18, v19
	ds_read_b64_tr_b16 v[102:103], v92 offset:13824
	ds_read_b64_tr_b16 v[104:105], v92 offset:16128
	s_waitcnt lgkmcnt(2)
	v_mfma_f32_16x16x32_bf16 v[56:59], v[64:67], v[76:79], v[56:59]
	ds_read_b128 v[64:67], v106 offset:2304
	v_cvt_pk_bf16_f32 v60, v28, v29
	v_cvt_pk_bf16_f32 v61, v30, v31
	v_cvt_pk_bf16_f32 v62, v24, v25
	v_cvt_pk_bf16_f32 v63, v26, v27
	s_waitcnt lgkmcnt(0)
	v_mfma_f32_16x16x32_bf16 v[64:67], v[64:67], v[48:51], 0
	s_cmp_lt_i32 s73, 0
	s_cbranch_scc1 .Lhg3_w_nopf
	s_waitcnt vmcnt(18)
	s_branch .Lhg3_w_done

.Lhg3_w_done:
	v_and_b32_e32 v95, 0xffff0000, v53
	s_brev_b32 s66, 60
	s_add_u32 s82, s82, 64
	v_mfma_f32_16x16x32_bf16 v[56:59], v[102:105], v[60:63], v[56:59]
	ds_read_b128 v[80:83], v106 offset:2368
	ds_read_b64_tr_b16 v[104:105], v94 offset:32
	ds_read_b64_tr_b16 v[102:103], v92 offset:32
	s_addc_u32 s83, s83, 0
	s_waitcnt lgkmcnt(2)
	v_mfma_f32_16x16x32_bf16 v[64:67], v[80:83], v[44:47], v[64:67]
	ds_read_b64_tr_b16 v[80:81], v94 offset:2336
	ds_read_b64_tr_b16 v[82:83], v94 offset:4640
	s_cmpk_lg_i32 s82, 0x200
	s_waitcnt lgkmcnt(2)
	v_mfma_f32_16x16x32_bf16 v[64:67], v[102:105], v[72:75], v[64:67]
	s_waitcnt lgkmcnt(0)
	v_mfma_f32_16x16x32_bf16 v[64:67], v[80:83], v[68:71], v[64:67]
	ds_read_b64_tr_b16 v[80:81], v92 offset:9248
	ds_read_b64_tr_b16 v[82:83], v92 offset:11552
	s_waitcnt lgkmcnt(0)
	v_mfma_f32_16x16x32_bf16 v[64:67], v[80:83], v[76:79], v[64:67]
	ds_read_b64_tr_b16 v[80:81], v92 offset:13856
	ds_read_b64_tr_b16 v[82:83], v92 offset:16160
	ds_read_b128 v[102:105], v106 offset:4672
	s_waitcnt lgkmcnt(1)
	v_mfma_f32_16x16x32_bf16 v[64:67], v[80:83], v[60:63], v[64:67]
	ds_read_b128 v[80:83], v106 offset:4608
	s_waitcnt lgkmcnt(0)
	v_mfma_f32_16x16x32_bf16 v[80:83], v[80:83], v[48:51], 0
	v_mfma_f32_16x16x32_bf16 v[80:83], v[102:105], v[44:47], v[80:83]
	ds_read_b64_tr_b16 v[102:103], v92 offset:64
	ds_read_b64_tr_b16 v[104:105], v94 offset:64
	s_waitcnt lgkmcnt(0)
	v_mfma_f32_16x16x32_bf16 v[80:83], v[102:105], v[72:75], v[80:83]
	ds_read_b64_tr_b16 v[102:103], v94 offset:2368
	ds_read_b64_tr_b16 v[104:105], v94 offset:4672
	s_waitcnt lgkmcnt(0)
	v_mfma_f32_16x16x32_bf16 v[80:83], v[102:105], v[68:71], v[80:83]
	ds_read_b64_tr_b16 v[102:103], v92 offset:9280
	ds_read_b64_tr_b16 v[104:105], v92 offset:11584
	s_waitcnt lgkmcnt(0)
	v_mfma_f32_16x16x32_bf16 v[80:83], v[102:105], v[76:79], v[80:83]
	ds_read_b64_tr_b16 v[102:103], v92 offset:13888
	ds_read_b64_tr_b16 v[104:105], v92 offset:16192
	ds_read_b128 v[128:131], v106 offset:6976
	s_waitcnt lgkmcnt(1)
	v_mfma_f32_16x16x32_bf16 v[80:83], v[102:105], v[60:63], v[80:83]
	ds_read_b128 v[102:105], v106 offset:6912
	s_waitcnt lgkmcnt(0)
	v_mfma_f32_16x16x32_bf16 v[102:105], v[102:105], v[48:51], 0
	v_mfma_f32_16x16x32_bf16 v[102:105], v[128:131], v[44:47], v[102:105]
	ds_read_b64_tr_b16 v[128:129], v92 offset:96
	ds_read_b64_tr_b16 v[130:131], v94 offset:96
	s_waitcnt lgkmcnt(0)
	v_mfma_f32_16x16x32_bf16 v[72:75], v[128:131], v[72:75], v[102:105]
	s_nop 3
	ds_read_b64_tr_b16 v[102:103], v94 offset:2400
	ds_read_b64_tr_b16 v[104:105], v94 offset:4704
	v_lshlrev_b32_e32 v130, 2, v126
	v_lshlrev_b32_e32 v94, 16, v53
	s_waitcnt lgkmcnt(0)
	v_mfma_f32_16x16x32_bf16 v[68:71], v[102:105], v[68:71], v[72:75]
	s_nop 2
	ds_read_b64_tr_b16 v[72:73], v92 offset:9312
	ds_read_b64_tr_b16 v[74:75], v92 offset:11616
	s_waitcnt lgkmcnt(0)
	v_mfma_f32_16x16x32_bf16 v[68:71], v[72:75], v[76:79], v[68:71]
	ds_read_b64_tr_b16 v[72:73], v92 offset:13920
	ds_read_b64_tr_b16 v[74:75], v92 offset:16224
	v_lshlrev_b32_e32 v78, 16, v55
	v_and_b32_e32 v79, 0xffff0000, v55
	s_waitcnt lgkmcnt(0)
	v_mfma_f32_16x16x32_bf16 v[60:63], v[72:75], v[60:63], v[68:71]
	s_nop 2
	v_lshl_add_u32 v68, v101, 1, s94
	v_bfe_u32 v69, v56, 16, 1
	v_add3_u32 v56, v56, v69, s41
	v_mad_u64_u32 v[70:71], vcc, v100, s52, v[68:69]
	ds_write_b16_d16_hi v70, v56 offset:18432
	v_bfe_u32 v56, v57, 16, 1
	v_add3_u32 v56, v57, v56, s41
	ds_write_b16_d16_hi v70, v56 offset:18704
	v_bfe_u32 v56, v58, 16, 1
	v_add3_u32 v56, v58, v56, s41
	ds_write_b16_d16_hi v70, v56 offset:18976
	v_bfe_u32 v56, v59, 16, 1
	v_add3_u32 v56, v59, v56, s41
	ds_write_b16_d16_hi v70, v56 offset:19248
	v_bfe_u32 v56, v64, 16, 1
	v_add3_u32 v58, v64, v56, s41
	v_mad_u64_u32 v[56:57], vcc, v107, s58, v[68:69]
	v_bfe_u32 v57, v65, 16, 1
	v_add3_u32 v57, v65, v57, s41
	ds_write_b16_d16_hi v70, v57 offset:23056
	v_bfe_u32 v57, v66, 16, 1
	v_add3_u32 v57, v66, v57, s41
	ds_write_b16_d16_hi v70, v57 offset:23328
	v_bfe_u32 v57, v67, 16, 1
	v_add3_u32 v57, v67, v57, s41
	ds_write_b16_d16_hi v70, v57 offset:23600
	v_bfe_u32 v57, v80, 16, 1
	v_add3_u32 v57, v80, v57, s41
	ds_write_b16_d16_hi v56, v57 offset:22784
	v_bfe_u32 v57, v81, 16, 1
	v_add3_u32 v57, v81, v57, s41
	ds_write_b16_d16_hi v70, v57 offset:27408
	v_bfe_u32 v57, v82, 16, 1
	v_add3_u32 v57, v82, v57, s41
	ds_write_b16_d16_hi v70, v57 offset:27680
	v_bfe_u32 v57, v83, 16, 1
	v_add3_u32 v57, v83, v57, s41
	ds_write_b16_d16_hi v70, v57 offset:27952
	v_bfe_u32 v57, v60, 16, 1
	v_add3_u32 v57, v60, v57, s41
	ds_write_b16_d16_hi v56, v58 offset:18432
	ds_write_b16_d16_hi v56, v57 offset:27136
	v_bfe_u32 v56, v61, 16, 1
	v_add3_u32 v56, v61, v56, s41
	ds_write_b16_d16_hi v70, v56 offset:31760
	v_bfe_u32 v56, v62, 16, 1
	v_add3_u32 v56, v62, v56, s41
	ds_write_b16_d16_hi v70, v56 offset:32032
	v_bfe_u32 v56, v63, 16, 1
	v_add3_u32 v56, v63, v56, s41
	ds_write_b16_d16_hi v70, v56 offset:32304
	v_add_u32_e32 v60, 0, v84
	s_waitcnt lgkmcnt(0)
	s_barrier
	v_add_u32_e32 v56, v60, v97
	ds_read_b128 v[56:59], v56 offset:18432
	s_cselect_b32 s99, 1, 0
	s_cmp_lg_u32 s82, 64
	s_cbranch_scc1 .Lhg3_og_skip
	global_load_dwordx4 v[244:247], v130, s[42:43] offset:16
	global_load_dwordx4 v[240:243], v130, s[42:43]
	s_waitcnt vmcnt(0)
.Lhg3_og_skip:
	s_cmp_lg_u32 s99, 0
	v_add_u32_e32 v53, v60, v96
	ds_read_b128 v[72:75], v53 offset:18432
	s_waitcnt lgkmcnt(1)
	v_and_b32_e32 v101, 0xffff0000, v56
	v_lshlrev_b32_e32 v92, 16, v57
	v_and_b32_e32 v93, 0xffff0000, v57
	s_waitcnt lgkmcnt(0)
	v_and_b32_e32 v127, 0xffff0000, v72
	v_lshlrev_b32_e32 v100, 16, v56
	v_lshlrev_b32_e32 v104, 16, v73
	v_and_b32_e32 v105, 0xffff0000, v73
	v_lshlrev_b32_e32 v126, 16, v72
	v_mov_b32_e32 v128, v127
	v_mov_b32_e32 v129, v101
	v_pk_mul_f32 v[96:97], v[92:93], v[92:93]
	v_pk_mul_f32 v[106:107], v[104:105], v[104:105]
	v_mov_b32_e32 v72, v126
	v_mov_b32_e32 v73, v100
	v_pk_mul_f32 v[128:129], v[128:129], v[128:129]
	v_lshlrev_b32_e32 v82, 16, v58
	v_and_b32_e32 v83, 0xffff0000, v58
	v_lshlrev_b32_e32 v62, 16, v74
	v_and_b32_e32 v63, 0xffff0000, v74
	v_pk_fma_f32 v[72:73], v[72:73], v[72:73], v[128:129]
	v_mov_b32_e32 v128, v106
	v_mov_b32_e32 v129, v96
	v_lshlrev_b32_e32 v76, 16, v59
	v_and_b32_e32 v77, 0xffff0000, v59
	v_lshlrev_b32_e32 v58, 16, v54
	v_and_b32_e32 v59, 0xffff0000, v54
	v_pk_mul_f32 v[54:55], v[82:83], v[82:83]
	v_lshlrev_b32_e32 v60, 16, v75
	v_and_b32_e32 v61, 0xffff0000, v75
	v_pk_mul_f32 v[74:75], v[62:63], v[62:63]
	v_pk_add_f32 v[72:73], v[128:129], v[72:73]
	v_mov_b32_e32 v96, v107
	v_pk_add_f32 v[72:73], v[96:97], v[72:73]
	v_mov_b32_e32 v96, v74
	v_mov_b32_e32 v97, v54
	v_pk_mul_f32 v[80:81], v[76:77], v[76:77]
	v_pk_mul_f32 v[102:103], v[60:61], v[60:61]
	v_pk_add_f32 v[72:73], v[96:97], v[72:73]
	v_mov_b32_e32 v54, v75
	v_pk_add_f32 v[54:55], v[54:55], v[72:73]
	v_mov_b32_e32 v72, v102
	v_mov_b32_e32 v73, v80
	v_pk_add_f32 v[54:55], v[72:73], v[54:55]
	v_mov_b32_e32 v80, v103
	v_pk_add_f32 v[54:55], v[80:81], v[54:55]
	v_mov_b32_e32 v73, v85
	v_mov_b32_e32 v72, v85
	v_lshlrev_b32_e32 v56, 16, v52
	v_mov_b32_dpp v73, v55 quad_perm:[1,0,3,2] row_mask:0xf bank_mask:0xf
	v_mov_b32_dpp v72, v54 quad_perm:[1,0,3,2] row_mask:0xf bank_mask:0xf
	v_pk_add_f32 v[54:55], v[54:55], v[72:73]
	v_mov_b32_e32 v73, v85
	v_mov_b32_e32 v72, v85
	v_and_b32_e32 v57, 0xffff0000, v52
	v_mov_b32_dpp v73, v55 quad_perm:[2,3,0,1] row_mask:0xf bank_mask:0xf
	v_mov_b32_dpp v72, v54 quad_perm:[2,3,0,1] row_mask:0xf bank_mask:0xf
	v_pk_add_f32 v[54:55], v[54:55], v[72:73]
	v_mov_b32_e32 v73, v85
	v_mov_b32_e32 v72, v85
	s_nop 0
	v_mov_b32_dpp v73, v55 row_half_mirror row_mask:0xf bank_mask:0xf
	v_mov_b32_dpp v72, v54 row_half_mirror row_mask:0xf bank_mask:0xf
	v_pk_add_f32 v[54:55], v[54:55], v[72:73]
	v_mov_b32_e32 v73, v85
	v_mov_b32_e32 v72, v85
	s_nop 0
	v_mov_b32_dpp v73, v55 row_mirror row_mask:0xf bank_mask:0xf
	v_mov_b32_dpp v72, v54 row_mirror row_mask:0xf bank_mask:0xf
	v_pk_add_f32 v[54:55], v[54:55], v[72:73]
	s_nop 0
	v_pk_fma_f32 v[72:73], v[54:55], s[66:67], v[86:87] op_sel_hi:[1,0,0]
	s_nop 0
	v_mul_f32_e32 v53, 0x4b800000, v73
	v_cmp_gt_f32_e32 vcc, s97, v73
	s_nop 1
	v_cndmask_b32_e32 v53, v73, v53, vcc
	v_rsq_f32_e32 v54, v53
	v_lshl_add_u64 v[52:53], s[18:19], 0, v[90:91]
	v_lshl_add_u64 v[74:75], v[52:53], 0, v[84:85]
	v_mul_f32_e32 v52, 0x45800000, v54
	v_cndmask_b32_e32 v52, v54, v52, vcc
	v_pk_mul_f32 v[54:55], v[52:53], v[100:101] op_sel_hi:[0,1]
	v_pk_mul_f32 v[54:55], v[240:241], v[54:55]
	v_pk_mul_f32 v[68:69], v[52:53], v[82:83] op_sel_hi:[0,1]
	v_pk_mul_f32 v[54:55], v[54:55], v[56:57]
	v_pk_mul_f32 v[56:57], v[52:53], v[92:93] op_sel_hi:[0,1]
	v_pk_mul_f32 v[52:53], v[52:53], v[76:77] op_sel_hi:[0,1]
	v_pk_mul_f32 v[56:57], v[242:243], v[56:57]
	v_pk_mul_f32 v[64:65], v[244:245], v[68:69]
	v_pk_mul_f32 v[52:53], v[246:247], v[52:53]
	v_pk_mul_f32 v[56:57], v[56:57], v[94:95]
	v_pk_mul_f32 v[58:59], v[64:65], v[58:59]
	v_pk_mul_f32 v[64:65], v[52:53], v[78:79]
	v_cvt_pk_bf16_f32 v52, v54, v55
	v_cvt_pk_bf16_f32 v53, v56, v57
	v_cvt_pk_bf16_f32 v54, v58, v59
	v_cvt_pk_bf16_f32 v55, v64, v65
	global_store_dwordx4 v[74:75], v[52:55], off
	s_nop 0
	v_lshlrev_b32_e32 v64, 16, v42
	v_and_b32_e32 v65, 0xffff0000, v42
	v_cmp_gt_f32_e32 vcc, s97, v72
	v_mul_f32_e32 v42, 0x4b800000, v72
	v_lshlrev_b32_e32 v68, 16, v40
	v_cndmask_b32_e32 v42, v72, v42, vcc
	v_rsq_f32_e32 v42, v42
	v_and_b32_e32 v69, 0xffff0000, v40
	v_lshlrev_b32_e32 v66, 16, v41
	v_and_b32_e32 v67, 0xffff0000, v41
	v_mul_f32_e32 v40, 0x45800000, v42
	v_cndmask_b32_e32 v42, v42, v40, vcc
	v_pk_mul_f32 v[40:41], v[42:43], v[126:127] op_sel_hi:[0,1]
	v_add3_u32 v71, 0, v98, v99
	v_pk_mul_f32 v[62:63], v[42:43], v[62:63] op_sel_hi:[0,1]
	v_pk_mul_f32 v[40:41], v[240:241], v[40:41]
	v_pk_mul_f32 v[56:57], v[42:43], v[104:105] op_sel_hi:[0,1]
	v_pk_mul_f32 v[40:41], v[40:41], v[68:69]
	v_pk_mul_f32 v[68:69], v[242:243], v[56:57]
	v_and_b32_e32 v56, -16, v125
	v_add_u32_e32 v56, 0, v56
	v_add_u32_e32 v70, 0x19800, v56
	ds_read_b128 v[56:59], v71 offset:55296
	ds_read_b128 v[72:75], v70
	v_pk_mul_f32 v[76:77], v[68:69], v[66:67]
	ds_read_b128 v[66:69], v71 offset:55360
	v_pk_mul_f32 v[52:53], v[244:245], v[62:63]
	v_cvt_pk_bf16_f32 v40, v40, v41
	s_waitcnt lgkmcnt(1)
	v_pk_mul_f32 v[0:1], v[0:1], v[72:73]
	v_pk_mul_f32 v[2:3], v[2:3], v[74:75]
	ds_read_b128 v[72:75], v71 offset:57600
	v_pk_mul_f32 v[78:79], v[52:53], v[64:65]
	v_mfma_f32_16x16x32_bf16 v[0:3], v[56:59], v[48:51], v[0:3]
	ds_read_b128 v[56:59], v70 offset:64
	v_pk_mul_f32 v[52:53], v[42:43], v[60:61] op_sel_hi:[0,1]
	ds_read_b128 v[60:63], v71 offset:57664
	s_waitcnt lgkmcnt(3)
	v_mfma_f32_16x16x32_bf16 v[0:3], v[66:69], v[44:47], v[0:3]
	v_lshlrev_b32_e32 v42, 16, v43
	s_waitcnt lgkmcnt(1)
	v_pk_mul_f32 v[4:5], v[4:5], v[56:57]
	v_pk_mul_f32 v[6:7], v[6:7], v[58:59]
	ds_read_b128 v[56:59], v71 offset:59904
	ds_read_b128 v[64:67], v70 offset:128
	v_mfma_f32_16x16x32_bf16 v[4:7], v[72:75], v[48:51], v[4:7]
	ds_read_b128 v[72:75], v71 offset:59968
	v_and_b32_e32 v43, 0xffff0000, v43
	v_pk_mul_f32 v[52:53], v[246:247], v[52:53]
	s_waitcnt lgkmcnt(3)
	v_mfma_f32_16x16x32_bf16 v[4:7], v[60:63], v[44:47], v[4:7]
	ds_read_b128 v[60:63], v71 offset:62208
	s_waitcnt lgkmcnt(2)
	v_pk_mul_f32 v[12:13], v[12:13], v[64:65]
	v_pk_mul_f32 v[14:15], v[14:15], v[66:67]
	v_pk_mul_f32 v[80:81], v[52:53], v[42:43]
	ds_read_b128 v[52:55], v71 offset:62272
	v_mfma_f32_16x16x32_bf16 v[12:15], v[56:59], v[48:51], v[12:15]
	ds_read_b128 v[56:59], v70 offset:192
	v_cvt_pk_bf16_f32 v41, v76, v77
	v_cvt_pk_bf16_f32 v42, v78, v79
	s_waitcnt lgkmcnt(3)
	v_mfma_f32_16x16x32_bf16 v[12:15], v[72:75], v[44:47], v[12:15]
	v_add_u32_e32 v72, 0xd800, v71
	s_waitcnt lgkmcnt(0)
	v_pk_mul_f32 v[8:9], v[8:9], v[56:57]
	v_pk_mul_f32 v[10:11], v[10:11], v[58:59]
	v_cvt_pk_bf16_f32 v43, v80, v81
	s_nop 0
	v_mfma_f32_16x16x32_bf16 v[8:11], v[60:63], v[48:51], v[8:11]
	ds_read_b128 v[56:59], v71 offset:64512
	ds_read_b128 v[60:63], v70 offset:256
	ds_read_b128 v[64:67], v71 offset:64576
	s_waitcnt lgkmcnt(1)
	v_pk_mul_f32 v[20:21], v[20:21], v[60:61]
	v_pk_mul_f32 v[22:23], v[22:23], v[62:63]
	v_mfma_f32_16x16x32_bf16 v[8:11], v[52:55], v[44:47], v[8:11]
	ds_read_b128 v[52:55], v72 offset:11520
	v_lshl_add_u64 v[60:61], s[18:19], 0, v[88:89]
	v_lshl_add_u64 v[60:61], v[60:61], 0, v[84:85]
	v_mfma_f32_16x16x32_bf16 v[20:23], v[56:59], v[48:51], v[20:23]
	ds_read_b128 v[56:59], v70 offset:320
	s_waitcnt lgkmcnt(0)
	v_pk_mul_f32 v[16:17], v[16:17], v[56:57]
	v_mfma_f32_16x16x32_bf16 v[20:23], v[64:67], v[44:47], v[20:23]
	ds_read_b128 v[62:65], v72 offset:11584
	v_pk_mul_f32 v[18:19], v[18:19], v[58:59]
	ds_read_b128 v[66:69], v72 offset:13824
	ds_read_b128 v[56:59], v70 offset:384
	v_mfma_f32_16x16x32_bf16 v[16:19], v[52:55], v[48:51], v[16:19]
	ds_read_b128 v[52:55], v72 offset:13888
	global_store_dwordx4 v[60:61], v[40:43], off
	s_waitcnt lgkmcnt(1)
	v_pk_mul_f32 v[28:29], v[28:29], v[56:57]
	v_pk_mul_f32 v[30:31], v[30:31], v[58:59]
	ds_read_b128 v[56:59], v72 offset:16128
	v_mfma_f32_16x16x32_bf16 v[16:19], v[62:65], v[44:47], v[16:19]
	ds_read_b128 v[62:65], v70 offset:448
	s_waitcnt lgkmcnt(0)
	v_pk_mul_f32 v[24:25], v[24:25], v[62:63]
	v_mfma_f32_16x16x32_bf16 v[28:31], v[66:69], v[48:51], v[28:31]
	ds_read_b128 v[66:69], v72 offset:16192
	v_pk_mul_f32 v[26:27], v[26:27], v[64:65]
	v_mfma_f32_16x16x32_bf16 v[28:31], v[52:55], v[44:47], v[28:31]
	s_nop 0
	v_mfma_f32_16x16x32_bf16 v[24:27], v[56:59], v[48:51], v[24:27]
	s_waitcnt lgkmcnt(0)
	v_mfma_f32_16x16x32_bf16 v[24:27], v[66:69], v[44:47], v[24:27]
	s_cbranch_scc0 .LBB0_1404
